# accumulator zeroing with v_mov_b64 (half the instructions) on top of the sc1 stores
# baseline (speedup 1.0000x reference)
.LBB0_99:
	s_ashr_i32 s43, s42, 31
	s_lshl_b64 s[20:21], s[42:43], 21
	v_cmp_lt_i64_e32 vcc, s[44:45], v[186:187]
	s_add_u32 s44, s70, s20
	s_addc_u32 s45, s71, s21
	s_and_b64 s[20:21], vcc, exec
	s_cselect_b32 s43, s45, s49
	s_cselect_b32 s24, s44, s48
	s_ashr_i32 s1, s0, 31
	s_lshl_b64 s[20:21], s[0:1], 21
	v_readlane_b32 s46, v254, 27
	v_readlane_b32 s47, v254, 28
	s_add_u32 s46, s46, s20
	s_addc_u32 s47, s47, s21
	s_and_b64 s[20:21], vcc, exec
	s_cselect_b32 s1, s47, s29
	s_cselect_b32 s25, s46, s28
	s_add_u32 s48, s48, 0x100080
	s_addc_u32 s49, s49, 0
	s_add_u32 vcc_lo, s28, 0x100
	v_mov_b32_e32 v0, 0
	s_addc_u32 vcc_hi, s29, 0
	s_mov_b32 s20, -2
	v_mov_b32_e32 v1, v0
	v_mov_b64_e32 v[2:3], 0
	v_mov_b64_e32 v[4:5], 0
	v_mov_b64_e32 v[6:7], 0
	v_mov_b64_e32 v[16:17], 0
	v_mov_b64_e32 v[18:19], 0
	v_mov_b64_e32 v[20:21], 0
	v_mov_b64_e32 v[22:23], 0
	v_mov_b64_e32 v[32:33], 0
	v_mov_b64_e32 v[34:35], 0
	v_mov_b64_e32 v[36:37], 0
	v_mov_b64_e32 v[38:39], 0
	v_mov_b64_e32 v[48:49], 0
	v_mov_b64_e32 v[50:51], 0
	v_mov_b64_e32 v[52:53], 0
	v_mov_b64_e32 v[54:55], 0
	v_mov_b64_e32 v[8:9], 0
	v_mov_b64_e32 v[10:11], 0
	v_mov_b64_e32 v[12:13], 0
	v_mov_b64_e32 v[14:15], 0
	v_mov_b64_e32 v[24:25], 0
	v_mov_b64_e32 v[26:27], 0
	v_mov_b64_e32 v[28:29], 0
	v_mov_b64_e32 v[30:31], 0
	v_mov_b64_e32 v[40:41], 0
	v_mov_b64_e32 v[42:43], 0
	v_mov_b64_e32 v[44:45], 0
	v_mov_b64_e32 v[46:47], 0
	v_mov_b64_e32 v[56:57], 0
	v_mov_b64_e32 v[58:59], 0
	v_mov_b64_e32 v[60:61], 0
	v_mov_b64_e32 v[62:63], 0
	v_mov_b64_e32 v[64:65], 0
	v_mov_b64_e32 v[66:67], 0
	v_mov_b64_e32 v[68:69], 0
	v_mov_b64_e32 v[70:71], 0
	v_mov_b64_e32 v[80:81], 0
	v_mov_b64_e32 v[82:83], 0
	v_mov_b64_e32 v[84:85], 0
	v_mov_b64_e32 v[86:87], 0
	v_mov_b64_e32 v[96:97], 0
	v_mov_b64_e32 v[98:99], 0
	v_mov_b64_e32 v[100:101], 0
	v_mov_b64_e32 v[102:103], 0
	v_mov_b64_e32 v[136:137], 0
	v_mov_b64_e32 v[138:139], 0
	v_mov_b64_e32 v[140:141], 0
	v_mov_b64_e32 v[142:143], 0
	v_mov_b64_e32 v[72:73], 0
	v_mov_b64_e32 v[74:75], 0
	v_mov_b64_e32 v[76:77], 0
	v_mov_b64_e32 v[78:79], 0
	v_mov_b64_e32 v[88:89], 0
	v_mov_b64_e32 v[90:91], 0
	v_mov_b64_e32 v[92:93], 0
	v_mov_b64_e32 v[94:95], 0
	v_mov_b64_e32 v[104:105], 0
	v_mov_b64_e32 v[106:107], 0
	v_mov_b64_e32 v[108:109], 0
	v_mov_b64_e32 v[110:111], 0
	v_mov_b64_e32 v[144:145], 0
	v_mov_b64_e32 v[146:147], 0
	v_mov_b64_e32 v[148:149], 0
	v_mov_b64_e32 v[150:151], 0

.LBB0_146:
	s_ashr_i32 s43, s42, 31
	s_lshl_b64 s[20:21], s[42:43], 19
	v_cmp_lt_i64_e32 vcc, s[44:45], v[190:191]
	s_add_u32 s44, s68, s20
	s_addc_u32 s45, s69, s21
	s_and_b64 s[20:21], vcc, exec
	s_cselect_b32 s43, s45, s1
	s_cselect_b32 s24, s44, s0
	s_ashr_i32 s41, s40, 31
	s_lshl_b64 s[20:21], s[40:41], 19
	v_readlane_b32 s46, v253, 62
	v_readlane_b32 s47, v253, 63
	s_add_u32 s46, s46, s20
	s_addc_u32 s47, s47, s21
	s_and_b64 s[20:21], vcc, exec
	s_cselect_b32 s25, s47, s29
	s_cselect_b32 s41, s46, s28
	s_add_u32 s0, s0, 0x40080
	s_addc_u32 s1, s1, 0
	s_add_u32 vcc_lo, s28, 0x100
	v_mov_b32_e32 v0, 0
	s_addc_u32 vcc_hi, s29, 0
	s_mov_b32 s20, -2
	v_mov_b32_e32 v1, v0
	v_mov_b64_e32 v[2:3], 0
	v_mov_b64_e32 v[4:5], 0
	v_mov_b64_e32 v[6:7], 0
	v_mov_b64_e32 v[16:17], 0
	v_mov_b64_e32 v[18:19], 0
	v_mov_b64_e32 v[20:21], 0
	v_mov_b64_e32 v[22:23], 0
	v_mov_b64_e32 v[32:33], 0
	v_mov_b64_e32 v[34:35], 0
	v_mov_b64_e32 v[36:37], 0
	v_mov_b64_e32 v[38:39], 0
	v_mov_b64_e32 v[48:49], 0
	v_mov_b64_e32 v[50:51], 0
	v_mov_b64_e32 v[52:53], 0
	v_mov_b64_e32 v[54:55], 0
	v_mov_b64_e32 v[8:9], 0
	v_mov_b64_e32 v[10:11], 0
	v_mov_b64_e32 v[12:13], 0
	v_mov_b64_e32 v[14:15], 0
	v_mov_b64_e32 v[24:25], 0
	v_mov_b64_e32 v[26:27], 0
	v_mov_b64_e32 v[28:29], 0
	v_mov_b64_e32 v[30:31], 0
	v_mov_b64_e32 v[40:41], 0
	v_mov_b64_e32 v[42:43], 0
	v_mov_b64_e32 v[44:45], 0
	v_mov_b64_e32 v[46:47], 0
	v_mov_b64_e32 v[56:57], 0
	v_mov_b64_e32 v[58:59], 0
	v_mov_b64_e32 v[60:61], 0
	v_mov_b64_e32 v[62:63], 0
	v_mov_b64_e32 v[64:65], 0
	v_mov_b64_e32 v[66:67], 0
	v_mov_b64_e32 v[68:69], 0
	v_mov_b64_e32 v[70:71], 0
	v_mov_b64_e32 v[80:81], 0
	v_mov_b64_e32 v[82:83], 0
	v_mov_b64_e32 v[84:85], 0
	v_mov_b64_e32 v[86:87], 0
	v_mov_b64_e32 v[96:97], 0
	v_mov_b64_e32 v[98:99], 0
	v_mov_b64_e32 v[100:101], 0
	v_mov_b64_e32 v[102:103], 0
	v_mov_b64_e32 v[112:113], 0
	v_mov_b64_e32 v[114:115], 0
	v_mov_b64_e32 v[116:117], 0
	v_mov_b64_e32 v[118:119], 0
	v_mov_b64_e32 v[72:73], 0
	v_mov_b64_e32 v[74:75], 0
	v_mov_b64_e32 v[76:77], 0
	v_mov_b64_e32 v[78:79], 0
	v_mov_b64_e32 v[88:89], 0
	v_mov_b64_e32 v[90:91], 0
	v_mov_b64_e32 v[92:93], 0
	v_mov_b64_e32 v[94:95], 0
	v_mov_b64_e32 v[104:105], 0
	v_mov_b64_e32 v[106:107], 0
	v_mov_b64_e32 v[108:109], 0
	v_mov_b64_e32 v[110:111], 0
	v_mov_b64_e32 v[120:121], 0
	v_mov_b64_e32 v[122:123], 0
	v_mov_b64_e32 v[124:125], 0
	v_mov_b64_e32 v[126:127], 0

.LBB0_169:
	s_ashr_i32 s43, s42, 31
	s_lshl_b64 s[20:21], s[42:43], 19
	v_readlane_b32 s24, v254, 43
	v_cmp_lt_i64_e32 vcc, s[44:45], v[186:187]
	v_readlane_b32 s25, v254, 44
	s_add_u32 s44, s24, s20
	s_addc_u32 s45, s25, s21
	s_and_b64 s[20:21], vcc, exec
	s_cselect_b32 s43, s45, s49
	s_cselect_b32 s24, s44, s48
	s_ashr_i32 s1, s0, 31
	s_lshl_b64 s[20:21], s[0:1], 19
	v_readlane_b32 s46, v254, 41
	v_readlane_b32 s47, v254, 42
	s_add_u32 s46, s46, s20
	s_addc_u32 s47, s47, s21
	s_and_b64 s[20:21], vcc, exec
	s_cselect_b32 s1, s47, s29
	s_cselect_b32 s25, s46, s28
	s_add_u32 s48, s48, 0x40080
	s_addc_u32 s49, s49, 0
	s_add_u32 vcc_lo, s28, 0x100
	v_mov_b32_e32 v0, 0
	s_mov_b64 s[92:93], s[74:75]
	s_addc_u32 vcc_hi, s29, 0
	s_mov_b32 s57, -2
	v_mov_b32_e32 v1, v0
	v_mov_b64_e32 v[2:3], 0
	v_mov_b64_e32 v[4:5], 0
	v_mov_b64_e32 v[6:7], 0
	v_mov_b64_e32 v[16:17], 0
	v_mov_b64_e32 v[18:19], 0
	v_mov_b64_e32 v[20:21], 0
	v_mov_b64_e32 v[22:23], 0
	v_mov_b64_e32 v[32:33], 0
	v_mov_b64_e32 v[34:35], 0
	v_mov_b64_e32 v[36:37], 0
	v_mov_b64_e32 v[38:39], 0
	v_mov_b64_e32 v[48:49], 0
	v_mov_b64_e32 v[50:51], 0
	v_mov_b64_e32 v[52:53], 0
	v_mov_b64_e32 v[54:55], 0
	v_mov_b64_e32 v[8:9], 0
	v_mov_b64_e32 v[10:11], 0
	v_mov_b64_e32 v[12:13], 0
	v_mov_b64_e32 v[14:15], 0
	v_mov_b64_e32 v[24:25], 0
	v_mov_b64_e32 v[26:27], 0
	v_mov_b64_e32 v[28:29], 0
	v_mov_b64_e32 v[30:31], 0
	v_mov_b64_e32 v[40:41], 0
	v_mov_b64_e32 v[42:43], 0
	v_mov_b64_e32 v[44:45], 0
	v_mov_b64_e32 v[46:47], 0
	v_mov_b64_e32 v[56:57], 0
	v_mov_b64_e32 v[58:59], 0
	v_mov_b64_e32 v[60:61], 0
	v_mov_b64_e32 v[62:63], 0
	v_mov_b64_e32 v[64:65], 0
	v_mov_b64_e32 v[66:67], 0
	v_mov_b64_e32 v[68:69], 0
	v_mov_b64_e32 v[70:71], 0
	v_mov_b64_e32 v[80:81], 0
	v_mov_b64_e32 v[82:83], 0
	v_mov_b64_e32 v[84:85], 0
	v_mov_b64_e32 v[86:87], 0
	v_mov_b64_e32 v[96:97], 0
	v_mov_b64_e32 v[98:99], 0
	v_mov_b64_e32 v[100:101], 0
	v_mov_b64_e32 v[102:103], 0
	v_mov_b64_e32 v[112:113], 0
	v_mov_b64_e32 v[114:115], 0
	v_mov_b64_e32 v[116:117], 0
	v_mov_b64_e32 v[118:119], 0
	v_mov_b64_e32 v[72:73], 0
	v_mov_b64_e32 v[74:75], 0
	v_mov_b64_e32 v[76:77], 0
	v_mov_b64_e32 v[78:79], 0
	v_mov_b64_e32 v[88:89], 0
	v_mov_b64_e32 v[90:91], 0
	v_mov_b64_e32 v[92:93], 0
	v_mov_b64_e32 v[94:95], 0
	v_mov_b64_e32 v[104:105], 0
	v_mov_b64_e32 v[106:107], 0
	v_mov_b64_e32 v[108:109], 0
	v_mov_b64_e32 v[110:111], 0
	v_mov_b64_e32 v[120:121], 0
	v_mov_b64_e32 v[122:123], 0
	v_mov_b64_e32 v[124:125], 0
	v_mov_b64_e32 v[126:127], 0

.LBB0_291:
	s_ashr_i32 s41, s40, 31
	v_mov_b64_e32 v[0:1], 0x400
	s_lshl_b64 s[20:21], s[40:41], 19
	v_readlane_b32 s24, v254, 15
	v_cmp_lt_i64_e32 vcc, s[42:43], v[0:1]
	v_readlane_b32 s25, v254, 16
	s_add_u32 s42, s24, s20
	s_addc_u32 s43, s25, s21
	s_and_b64 s[20:21], vcc, exec
	s_cselect_b32 s41, s43, s47
	s_cselect_b32 s24, s42, s46
	s_ashr_i32 s1, s0, 31
	s_lshl_b64 s[20:21], s[0:1], 19
	v_readlane_b32 s44, v254, 13
	v_readlane_b32 s45, v254, 14
	s_add_u32 s44, s44, s20
	s_addc_u32 s45, s45, s21
	s_and_b64 s[20:21], vcc, exec
	s_cselect_b32 s1, s45, s29
	s_cselect_b32 s25, s44, s28
	s_add_u32 s46, s46, 0x40080
	s_addc_u32 s47, s47, 0
	s_add_u32 s58, s28, 0x100
	v_mov_b32_e32 v0, 0
	s_addc_u32 s59, s29, 0
	s_mov_b32 vcc_lo, -2
	v_mov_b32_e32 v1, v0
	v_mov_b64_e32 v[2:3], 0
	v_mov_b64_e32 v[4:5], 0
	v_mov_b64_e32 v[6:7], 0
	v_mov_b64_e32 v[8:9], 0
	v_mov_b64_e32 v[10:11], 0
	v_mov_b64_e32 v[16:17], 0
	v_mov_b64_e32 v[18:19], 0
	v_mov_b64_e32 v[24:25], 0
	v_mov_b64_e32 v[26:27], 0
	v_mov_b64_e32 v[32:33], 0
	v_mov_b64_e32 v[34:35], 0
	v_mov_b64_e32 v[40:41], 0
	v_mov_b64_e32 v[42:43], 0
	v_mov_b64_e32 v[48:49], 0
	v_mov_b64_e32 v[50:51], 0
	v_mov_b64_e32 v[12:13], 0
	v_mov_b64_e32 v[14:15], 0
	v_mov_b64_e32 v[20:21], 0
	v_mov_b64_e32 v[22:23], 0
	v_mov_b64_e32 v[28:29], 0
	v_mov_b64_e32 v[30:31], 0
	v_mov_b64_e32 v[36:37], 0
	v_mov_b64_e32 v[38:39], 0
	v_mov_b64_e32 v[44:45], 0
	v_mov_b64_e32 v[46:47], 0
	v_mov_b64_e32 v[52:53], 0
	v_mov_b64_e32 v[54:55], 0
	v_mov_b64_e32 v[56:57], 0
	v_mov_b64_e32 v[58:59], 0
	v_mov_b64_e32 v[60:61], 0
	v_mov_b64_e32 v[62:63], 0
	v_mov_b64_e32 v[64:65], 0
	v_mov_b64_e32 v[66:67], 0
	v_mov_b64_e32 v[68:69], 0
	v_mov_b64_e32 v[70:71], 0
	v_mov_b64_e32 v[76:77], 0
	v_mov_b64_e32 v[78:79], 0
	v_mov_b64_e32 v[84:85], 0
	v_mov_b64_e32 v[86:87], 0
	v_mov_b64_e32 v[88:89], 0
	v_mov_b64_e32 v[90:91], 0
	v_mov_b64_e32 v[96:97], 0
	v_mov_b64_e32 v[98:99], 0
	v_mov_b64_e32 v[104:105], 0
	v_mov_b64_e32 v[106:107], 0
	v_mov_b64_e32 v[112:113], 0
	v_mov_b64_e32 v[114:115], 0
	v_mov_b64_e32 v[72:73], 0
	v_mov_b64_e32 v[74:75], 0
	v_mov_b64_e32 v[80:81], 0
	v_mov_b64_e32 v[82:83], 0
	v_mov_b64_e32 v[92:93], 0
	v_mov_b64_e32 v[94:95], 0
	v_mov_b64_e32 v[100:101], 0
	v_mov_b64_e32 v[102:103], 0
	v_mov_b64_e32 v[108:109], 0
	v_mov_b64_e32 v[110:111], 0
	v_mov_b64_e32 v[116:117], 0
	v_mov_b64_e32 v[118:119], 0
	v_mov_b64_e32 v[120:121], 0
	v_mov_b64_e32 v[122:123], 0
	v_mov_b64_e32 v[124:125], 0
	v_mov_b64_e32 v[126:127], 0

.LBB0_311:
	s_waitcnt lgkmcnt(3)
	v_mov_b32_e32 v0, 0
	s_mov_b32 s6, 0
	s_waitcnt lgkmcnt(1)
	v_mov_b32_e32 v5, 0
	v_mov_b32_e32 v17, 0
	v_mov_b32_e32 v1, v0
	v_mov_b64_e32 v[20:21], 0
	v_mov_b64_e32 v[18:19], 0
	v_mov_b64_e32 v[2:3], 0
	s_branch .LBB0_313

.LBB0_348:
	s_waitcnt lgkmcnt(3)
	v_mov_b32_e32 v0, 0
	s_mov_b32 s6, 0
	s_waitcnt lgkmcnt(1)
	v_mov_b32_e32 v5, 0
	v_mov_b32_e32 v19, 0
	v_mov_b32_e32 v1, v0
	v_mov_b64_e32 v[22:23], 0
	v_mov_b64_e32 v[20:21], 0
	v_mov_b64_e32 v[2:3], 0
	s_branch .LBB0_350
